# v15 + final RMSNorm: lane owns columns 256q+4lane so each load/store instruction of a wave is contiguous (1 KiB f32 stores instead of 64 scattered 16-byte pieces)
# speedup vs baseline: 1.0575x; 1.0144x over previous
.LBB0_1509:
	s_cmp_lt_i32 s30, 11
	s_cselect_b64 s[2:3], -1, 0
	s_and_b64 s[0:1], s[2:3], s[0:1]
	s_andn2_b64 vcc, exec, s[0:1]
	s_cbranch_vccnz .LBB0_1551
	v_lshrrev_b32_e32 v16, 6, v128
	s_waitcnt vmcnt(17)
	v_lshl_add_u32 v114, s22, 3, v16
	s_movk_i32 s0, 0x72b
	v_cmp_gt_i32_e32 vcc, s0, v114
	s_and_saveexec_b64 s[0:1], vcc
	s_cbranch_execz .LBB0_1551
	v_and_b32_e32 v0, 63, v128
	s_waitcnt vmcnt(10)
	v_lshlrev_b32_e32 v88, 3, v0
	v_mov_b32_e32 v89, 0
	v_lshl_add_u64 v[18:19], s[28:29], 0, v[88:89]
	v_lshlrev_b32_e32 v88, 4, v0
	s_waitcnt lgkmcnt(0)
	global_load_dwordx4 v[0:3], v88, s[24:25] offset:3072
	global_load_dwordx4 v[4:7], v88, s[24:25] offset:2048
	global_load_dwordx4 v[8:11], v88, s[24:25] offset:1024
	global_load_dwordx4 v[12:15], v88, s[24:25]
	s_mov_b64 s[0:1], 0x3000000
	s_lshl_b32 s10, s34, 3
	v_lshl_add_u64 v[90:91], v[18:19], 0, s[0:1]
	s_mul_i32 s0, s22, 0x48
	s_add_u32 s2, s28, 0x2f30c00
	v_mad_u32_u24 v16, v16, 9, s0
	s_addc_u32 s3, s29, 0
	v_lshl_add_u64 v[92:93], s[26:27], 0, v[88:89]
	v_add_u32_e32 v88, 0xffffc000, v16
	s_mul_i32 s11, s34, 0x48
	s_mov_b64 s[4:5], 0
	s_movk_i32 s12, 0x71c
	s_mov_b64 s[6:7], 0x1000000
	v_mov_b32_e32 v115, 0x358637bd
	s_mov_b32 s13, 0x800000
	s_movk_i32 s14, 0x71b
	s_movk_i32 s15, 0x72a
	s_branch .LBB0_1514
.LBB0_1512:
	s_or_b64 exec, exec, s[0:1]
	v_fmamk_f32 v26, v116, 0x3a800000, v115
	v_mul_f32_e32 v27, 0x4b800000, v26
	v_cmp_gt_f32_e32 vcc, s13, v26
	v_lshl_add_u64 v[28:29], v[24:25], 2, v[92:93]
	v_lshlrev_b32_e32 v24, 16, v20
	v_cndmask_b32_e32 v26, v26, v27, vcc
	v_rsq_f32_e32 v26, v26
	s_nop 0
	v_mul_f32_e32 v25, 0x45800000, v26
	v_cndmask_b32_e32 v30, v26, v25, vcc
	v_and_b32_e32 v25, 0xffff0000, v20
	v_lshlrev_b32_e32 v20, 16, v21
	v_and_b32_e32 v21, 0xffff0000, v21
	v_pk_mul_f32 v[20:21], v[30:31], v[20:21] op_sel_hi:[0,1]
	v_pk_mul_f32 v[26:27], v[14:15], v[20:21]
	v_lshlrev_b32_e32 v20, 16, v22
	v_and_b32_e32 v21, 0xffff0000, v22
	v_lshlrev_b32_e32 v22, 16, v23
	v_and_b32_e32 v23, 0xffff0000, v23
	v_pk_mul_f32 v[20:21], v[30:31], v[20:21] op_sel_hi:[0,1]
	v_pk_mul_f32 v[22:23], v[30:31], v[22:23] op_sel_hi:[0,1]
	v_pk_mul_f32 v[20:21], v[8:9], v[20:21]
	v_pk_mul_f32 v[22:23], v[10:11], v[22:23]
	global_store_dwordx4 v[28:29], v[20:23], off offset:1024
	v_pk_mul_f32 v[24:25], v[30:31], v[24:25] op_sel_hi:[0,1]
	v_pk_mul_f32 v[24:25], v[12:13], v[24:25]
	v_lshlrev_b32_e32 v20, 16, v16
	v_and_b32_e32 v21, 0xffff0000, v16
	v_lshlrev_b32_e32 v16, 16, v17
	v_and_b32_e32 v17, 0xffff0000, v17
	v_pk_mul_f32 v[16:17], v[30:31], v[16:17] op_sel_hi:[0,1]
	v_pk_mul_f32 v[22:23], v[6:7], v[16:17]
	v_lshlrev_b32_e32 v16, 16, v18
	v_and_b32_e32 v17, 0xffff0000, v18
	v_lshlrev_b32_e32 v18, 16, v19
	v_and_b32_e32 v19, 0xffff0000, v19
	v_pk_mul_f32 v[20:21], v[30:31], v[20:21] op_sel_hi:[0,1]
	v_pk_mul_f32 v[16:17], v[30:31], v[16:17] op_sel_hi:[0,1]
	v_pk_mul_f32 v[18:19], v[30:31], v[18:19] op_sel_hi:[0,1]
	v_pk_mul_f32 v[20:21], v[4:5], v[20:21]
	v_pk_mul_f32 v[16:17], v[0:1], v[16:17]
	v_pk_mul_f32 v[18:19], v[2:3], v[18:19]
	global_store_dwordx4 v[28:29], v[24:27], off
	global_store_dwordx4 v[28:29], v[20:23], off offset:2048
	global_store_dwordx4 v[28:29], v[16:19], off offset:3072

.LBB0_1514:
	v_add_u32_e32 v110, 0x4000, v88
	v_ashrrev_i32_e32 v111, 31, v110
	v_lshlrev_b64 v[16:17], 11, v[110:111]
	v_add_u32_e32 v108, 0x4001, v88
	v_lshl_add_u64 v[16:17], v[90:91], 0, v[16:17]
	v_ashrrev_i32_e32 v109, 31, v108
	global_load_dwordx2 v[80:81], v[16:17], off offset:1024
	global_load_dwordx2 v[82:83], v[16:17], off offset:1536
	global_load_dwordx2 v[84:85], v[16:17], off
	global_load_dwordx2 v[86:87], v[16:17], off offset:512
	v_lshlrev_b64 v[16:17], 11, v[108:109]
	v_add_u32_e32 v106, 0x4002, v88
	v_lshl_add_u64 v[16:17], v[90:91], 0, v[16:17]
	v_ashrrev_i32_e32 v107, 31, v106
	global_load_dwordx2 v[72:73], v[16:17], off offset:1024
	global_load_dwordx2 v[74:75], v[16:17], off offset:1536
	global_load_dwordx2 v[76:77], v[16:17], off
	global_load_dwordx2 v[78:79], v[16:17], off offset:512
	v_lshl_add_u64 v[16:17], v[108:109], 2, s[2:3]
	v_lshlrev_b64 v[18:19], 11, v[106:107]
	v_add_u32_e32 v104, 0x4003, v88
	v_lshl_add_u64 v[18:19], v[90:91], 0, v[18:19]
	global_load_dword v120, v[16:17], off
	global_load_dwordx2 v[68:69], v[18:19], off
	global_load_dwordx2 v[70:71], v[18:19], off offset:512
	v_lshl_add_u64 v[16:17], v[106:107], 2, s[2:3]
	v_ashrrev_i32_e32 v105, 31, v104
	global_load_dwordx2 v[64:65], v[18:19], off offset:1024
	global_load_dwordx2 v[66:67], v[18:19], off offset:1536
	global_load_dword v119, v[16:17], off
	v_lshlrev_b64 v[16:17], 11, v[104:105]
	v_add_u32_e32 v102, 0x4004, v88
	v_lshl_add_u64 v[16:17], v[90:91], 0, v[16:17]
	v_ashrrev_i32_e32 v103, 31, v102
	global_load_dwordx2 v[56:57], v[16:17], off offset:1024
	global_load_dwordx2 v[58:59], v[16:17], off offset:1536
	global_load_dwordx2 v[60:61], v[16:17], off
	global_load_dwordx2 v[62:63], v[16:17], off offset:512
	v_lshl_add_u64 v[16:17], v[104:105], 2, s[2:3]
	v_lshlrev_b64 v[18:19], 11, v[102:103]
	v_add_u32_e32 v100, 0x4005, v88
	v_lshl_add_u64 v[18:19], v[90:91], 0, v[18:19]
	global_load_dword v118, v[16:17], off
	global_load_dwordx2 v[52:53], v[18:19], off
	global_load_dwordx2 v[54:55], v[18:19], off offset:512
	v_lshl_add_u64 v[16:17], v[102:103], 2, s[2:3]
	v_ashrrev_i32_e32 v101, 31, v100
	v_add_u32_e32 v98, 0x4006, v88
	global_load_dwordx2 v[48:49], v[18:19], off offset:1024
	global_load_dwordx2 v[50:51], v[18:19], off offset:1536
	global_load_dword v117, v[16:17], off
	v_lshlrev_b64 v[16:17], 11, v[100:101]
	v_min_i32_e32 v18, 0x407f, v98
	v_lshl_add_u64 v[16:17], v[90:91], 0, v[16:17]
	v_ashrrev_i32_e32 v19, 31, v18
	global_load_dwordx2 v[40:41], v[16:17], off offset:1024
	global_load_dwordx2 v[42:43], v[16:17], off offset:1536
	global_load_dwordx2 v[44:45], v[16:17], off
	global_load_dwordx2 v[46:47], v[16:17], off offset:512
	v_lshl_add_u64 v[16:17], v[100:101], 2, s[2:3]
	v_lshlrev_b64 v[20:21], 11, v[18:19]
	v_lshl_add_u64 v[20:21], v[90:91], 0, v[20:21]
	global_load_dword v99, v[16:17], off
	global_load_dwordx2 v[36:37], v[20:21], off
	global_load_dwordx2 v[38:39], v[20:21], off offset:512
	v_lshl_add_u64 v[16:17], v[18:19], 2, s[2:3]
	v_add_u32_e32 v96, 0x4007, v88
	global_load_dwordx2 v[32:33], v[20:21], off offset:1024
	global_load_dwordx2 v[34:35], v[20:21], off offset:1536
	global_load_dword v97, v[16:17], off
	v_min_i32_e32 v16, 0x407f, v96
	v_ashrrev_i32_e32 v17, 31, v16
	v_lshlrev_b64 v[18:19], 11, v[16:17]
	v_lshl_add_u64 v[18:19], v[90:91], 0, v[18:19]
	v_add_u32_e32 v94, 0x4008, v88
	global_load_dwordx2 v[24:25], v[18:19], off offset:1024
	global_load_dwordx2 v[26:27], v[18:19], off offset:1536
	global_load_dwordx2 v[28:29], v[18:19], off
	global_load_dwordx2 v[30:31], v[18:19], off offset:512
	v_min_i32_e32 v18, 0x407f, v94
	v_ashrrev_i32_e32 v19, 31, v18
	v_lshlrev_b64 v[20:21], 11, v[18:19]
	v_lshl_add_u64 v[16:17], v[16:17], 2, s[2:3]
	v_lshl_add_u64 v[112:113], v[90:91], 0, v[20:21]
	global_load_dword v95, v[16:17], off
	global_load_dwordx2 v[20:21], v[112:113], off
	global_load_dwordx2 v[22:23], v[112:113], off offset:512
	v_lshl_add_u64 v[122:123], v[18:19], 2, s[2:3]
	v_lshl_add_u64 v[124:125], v[110:111], 2, s[2:3]
	global_load_dwordx2 v[16:17], v[112:113], off offset:1024
	global_load_dwordx2 v[18:19], v[112:113], off offset:1536
	global_load_dword v116, v[122:123], off
	global_load_dword v121, v[124:125], off
	v_cmp_lt_i32_e32 vcc, s12, v114
	s_and_saveexec_b64 s[0:1], vcc
	s_xor_b64 s[0:1], exec, s[0:1]
	v_lshlrev_b64 v[110:111], 10, v[88:89]
	v_lshl_add_u64 v[112:113], v[110:111], 0, s[6:7]
	s_andn2_saveexec_b64 s[0:1], s[0:1]
	v_lshlrev_b64 v[112:113], 10, v[110:111]
	s_or_b64 exec, exec, s[0:1]
	s_waitcnt vmcnt(0)
	v_fmamk_f32 v110, v121, 0x3a800000, v115
	v_mul_f32_e32 v111, 0x4b800000, v110
	v_cmp_gt_f32_e64 s[0:1], s13, v110
	v_lshl_add_u64 v[122:123], v[112:113], 2, v[92:93]
	s_nop 0
	v_cndmask_b32_e64 v110, v110, v111, s[0:1]
	v_rsq_f32_e32 v111, v110
	v_lshlrev_b32_e32 v110, 16, v84
	v_mul_f32_e32 v112, 0x45800000, v111
	v_cndmask_b32_e64 v124, v111, v112, s[0:1]
	v_and_b32_e32 v111, 0xffff0000, v84
	v_lshlrev_b32_e32 v84, 16, v85
	v_and_b32_e32 v85, 0xffff0000, v85
	v_pk_mul_f32 v[84:85], v[124:125], v[84:85] op_sel_hi:[0,1]
	v_pk_mul_f32 v[112:113], v[14:15], v[84:85]
	v_lshlrev_b32_e32 v84, 16, v86
	v_and_b32_e32 v85, 0xffff0000, v86
	v_lshlrev_b32_e32 v86, 16, v87
	v_and_b32_e32 v87, 0xffff0000, v87
	v_pk_mul_f32 v[84:85], v[124:125], v[84:85] op_sel_hi:[0,1]
	v_pk_mul_f32 v[86:87], v[124:125], v[86:87] op_sel_hi:[0,1]
	v_pk_mul_f32 v[84:85], v[8:9], v[84:85]
	v_pk_mul_f32 v[86:87], v[10:11], v[86:87]
	global_store_dwordx4 v[122:123], v[84:87], off offset:1024
	v_pk_mul_f32 v[110:111], v[124:125], v[110:111] op_sel_hi:[0,1]
	v_pk_mul_f32 v[110:111], v[12:13], v[110:111]
	v_lshlrev_b32_e32 v84, 16, v80
	v_and_b32_e32 v85, 0xffff0000, v80
	v_lshlrev_b32_e32 v80, 16, v81
	v_and_b32_e32 v81, 0xffff0000, v81
	v_pk_mul_f32 v[80:81], v[124:125], v[80:81] op_sel_hi:[0,1]
	v_pk_mul_f32 v[86:87], v[6:7], v[80:81]
	v_lshlrev_b32_e32 v80, 16, v82
	v_and_b32_e32 v81, 0xffff0000, v82
	v_lshlrev_b32_e32 v82, 16, v83
	v_and_b32_e32 v83, 0xffff0000, v83
	v_pk_mul_f32 v[84:85], v[124:125], v[84:85] op_sel_hi:[0,1]
	v_pk_mul_f32 v[80:81], v[124:125], v[80:81] op_sel_hi:[0,1]
	v_pk_mul_f32 v[82:83], v[124:125], v[82:83] op_sel_hi:[0,1]
	v_pk_mul_f32 v[84:85], v[4:5], v[84:85]
	v_pk_mul_f32 v[80:81], v[0:1], v[80:81]
	v_pk_mul_f32 v[82:83], v[2:3], v[82:83]
	global_store_dwordx4 v[122:123], v[110:113], off
	global_store_dwordx4 v[122:123], v[84:87], off offset:2048
	global_store_dwordx4 v[122:123], v[80:83], off offset:3072
	s_and_saveexec_b64 s[0:1], vcc
	s_xor_b64 s[0:1], exec, s[0:1]
	v_add_u32_e32 v80, 1, v88
	v_mov_b32_e32 v81, v89
	v_lshlrev_b64 v[80:81], 10, v[80:81]
	v_lshl_add_u64 v[80:81], v[80:81], 0, s[6:7]
	s_andn2_saveexec_b64 s[0:1], s[0:1]
	v_lshlrev_b64 v[80:81], 10, v[108:109]
	s_or_b64 exec, exec, s[0:1]
	v_fmamk_f32 v82, v120, 0x3a800000, v115
	v_mul_f32_e32 v83, 0x4b800000, v82
	v_cmp_gt_f32_e64 s[0:1], s13, v82
	v_lshl_add_u64 v[84:85], v[80:81], 2, v[92:93]
	v_lshlrev_b32_e32 v80, 16, v76
	v_cndmask_b32_e64 v82, v82, v83, s[0:1]
	v_rsq_f32_e32 v82, v82
	s_nop 0
	v_mul_f32_e32 v81, 0x45800000, v82
	v_cndmask_b32_e64 v86, v82, v81, s[0:1]
	v_and_b32_e32 v81, 0xffff0000, v76
	v_lshlrev_b32_e32 v76, 16, v77
	v_and_b32_e32 v77, 0xffff0000, v77
	v_pk_mul_f32 v[76:77], v[86:87], v[76:77] op_sel_hi:[0,1]
	v_pk_mul_f32 v[82:83], v[14:15], v[76:77]
	v_lshlrev_b32_e32 v76, 16, v78
	v_and_b32_e32 v77, 0xffff0000, v78
	v_lshlrev_b32_e32 v78, 16, v79
	v_and_b32_e32 v79, 0xffff0000, v79
	v_pk_mul_f32 v[76:77], v[86:87], v[76:77] op_sel_hi:[0,1]
	v_pk_mul_f32 v[78:79], v[86:87], v[78:79] op_sel_hi:[0,1]
	v_pk_mul_f32 v[76:77], v[8:9], v[76:77]
	v_pk_mul_f32 v[78:79], v[10:11], v[78:79]
	global_store_dwordx4 v[84:85], v[76:79], off offset:1024
	v_pk_mul_f32 v[80:81], v[86:87], v[80:81] op_sel_hi:[0,1]
	v_pk_mul_f32 v[80:81], v[12:13], v[80:81]
	v_lshlrev_b32_e32 v76, 16, v72
	v_and_b32_e32 v77, 0xffff0000, v72
	v_lshlrev_b32_e32 v72, 16, v73
	v_and_b32_e32 v73, 0xffff0000, v73
	v_pk_mul_f32 v[72:73], v[86:87], v[72:73] op_sel_hi:[0,1]
	v_pk_mul_f32 v[78:79], v[6:7], v[72:73]
	v_lshlrev_b32_e32 v72, 16, v74
	v_and_b32_e32 v73, 0xffff0000, v74
	v_lshlrev_b32_e32 v74, 16, v75
	v_and_b32_e32 v75, 0xffff0000, v75
	v_pk_mul_f32 v[76:77], v[86:87], v[76:77] op_sel_hi:[0,1]
	v_pk_mul_f32 v[72:73], v[86:87], v[72:73] op_sel_hi:[0,1]
	v_pk_mul_f32 v[74:75], v[86:87], v[74:75] op_sel_hi:[0,1]
	v_pk_mul_f32 v[76:77], v[4:5], v[76:77]
	v_pk_mul_f32 v[72:73], v[0:1], v[72:73]
	v_pk_mul_f32 v[74:75], v[2:3], v[74:75]
	global_store_dwordx4 v[84:85], v[80:83], off
	global_store_dwordx4 v[84:85], v[76:79], off offset:2048
	global_store_dwordx4 v[84:85], v[72:75], off offset:3072
	s_and_saveexec_b64 s[0:1], vcc
	s_xor_b64 s[0:1], exec, s[0:1]
	v_add_u32_e32 v72, 2, v88
	v_mov_b32_e32 v73, v89
	v_lshlrev_b64 v[72:73], 10, v[72:73]
	v_lshl_add_u64 v[72:73], v[72:73], 0, s[6:7]
	s_andn2_saveexec_b64 s[0:1], s[0:1]
	v_lshlrev_b64 v[72:73], 10, v[106:107]
	s_or_b64 exec, exec, s[0:1]
	v_fmamk_f32 v74, v119, 0x3a800000, v115
	v_mul_f32_e32 v75, 0x4b800000, v74
	v_cmp_gt_f32_e64 s[0:1], s13, v74
	v_lshl_add_u64 v[76:77], v[72:73], 2, v[92:93]
	v_lshlrev_b32_e32 v72, 16, v68
	v_cndmask_b32_e64 v74, v74, v75, s[0:1]
	v_rsq_f32_e32 v74, v74
	s_nop 0
	v_mul_f32_e32 v73, 0x45800000, v74
	v_cndmask_b32_e64 v78, v74, v73, s[0:1]
	v_and_b32_e32 v73, 0xffff0000, v68
	v_lshlrev_b32_e32 v68, 16, v69
	v_and_b32_e32 v69, 0xffff0000, v69
	v_pk_mul_f32 v[68:69], v[78:79], v[68:69] op_sel_hi:[0,1]
	v_pk_mul_f32 v[74:75], v[14:15], v[68:69]
	v_lshlrev_b32_e32 v68, 16, v70
	v_and_b32_e32 v69, 0xffff0000, v70
	v_lshlrev_b32_e32 v70, 16, v71
	v_and_b32_e32 v71, 0xffff0000, v71
	v_pk_mul_f32 v[68:69], v[78:79], v[68:69] op_sel_hi:[0,1]
	v_pk_mul_f32 v[70:71], v[78:79], v[70:71] op_sel_hi:[0,1]
	v_pk_mul_f32 v[68:69], v[8:9], v[68:69]
	v_pk_mul_f32 v[70:71], v[10:11], v[70:71]
	global_store_dwordx4 v[76:77], v[68:71], off offset:1024
	v_pk_mul_f32 v[72:73], v[78:79], v[72:73] op_sel_hi:[0,1]
	v_pk_mul_f32 v[72:73], v[12:13], v[72:73]
	v_lshlrev_b32_e32 v68, 16, v64
	v_and_b32_e32 v69, 0xffff0000, v64
	v_lshlrev_b32_e32 v64, 16, v65
	v_and_b32_e32 v65, 0xffff0000, v65
	v_pk_mul_f32 v[64:65], v[78:79], v[64:65] op_sel_hi:[0,1]
	v_pk_mul_f32 v[70:71], v[6:7], v[64:65]
	v_lshlrev_b32_e32 v64, 16, v66
	v_and_b32_e32 v65, 0xffff0000, v66
	v_lshlrev_b32_e32 v66, 16, v67
	v_and_b32_e32 v67, 0xffff0000, v67
	v_pk_mul_f32 v[68:69], v[78:79], v[68:69] op_sel_hi:[0,1]
	v_pk_mul_f32 v[64:65], v[78:79], v[64:65] op_sel_hi:[0,1]
	v_pk_mul_f32 v[66:67], v[78:79], v[66:67] op_sel_hi:[0,1]
	v_pk_mul_f32 v[68:69], v[4:5], v[68:69]
	v_pk_mul_f32 v[64:65], v[0:1], v[64:65]
	v_pk_mul_f32 v[66:67], v[2:3], v[66:67]
	global_store_dwordx4 v[76:77], v[72:75], off
	global_store_dwordx4 v[76:77], v[68:71], off offset:2048
	global_store_dwordx4 v[76:77], v[64:67], off offset:3072
	s_and_saveexec_b64 s[0:1], vcc
	s_xor_b64 s[0:1], exec, s[0:1]
	v_add_u32_e32 v64, 3, v88
	v_mov_b32_e32 v65, v89
	v_lshlrev_b64 v[64:65], 10, v[64:65]
	v_lshl_add_u64 v[64:65], v[64:65], 0, s[6:7]
	s_andn2_saveexec_b64 s[0:1], s[0:1]
	v_lshlrev_b64 v[64:65], 10, v[104:105]
	s_or_b64 exec, exec, s[0:1]
	v_fmamk_f32 v66, v118, 0x3a800000, v115
	v_mul_f32_e32 v67, 0x4b800000, v66
	v_cmp_gt_f32_e32 vcc, s13, v66
	v_lshl_add_u64 v[68:69], v[64:65], 2, v[92:93]
	v_lshlrev_b32_e32 v64, 16, v60
	v_cndmask_b32_e32 v66, v66, v67, vcc
	v_rsq_f32_e32 v66, v66
	s_nop 0
	v_mul_f32_e32 v65, 0x45800000, v66
	v_cndmask_b32_e32 v70, v66, v65, vcc
	v_and_b32_e32 v65, 0xffff0000, v60
	v_lshlrev_b32_e32 v60, 16, v61
	v_and_b32_e32 v61, 0xffff0000, v61
	v_pk_mul_f32 v[60:61], v[70:71], v[60:61] op_sel_hi:[0,1]
	v_pk_mul_f32 v[66:67], v[14:15], v[60:61]
	v_lshlrev_b32_e32 v60, 16, v62
	v_and_b32_e32 v61, 0xffff0000, v62
	v_lshlrev_b32_e32 v62, 16, v63
	v_and_b32_e32 v63, 0xffff0000, v63
	v_pk_mul_f32 v[60:61], v[70:71], v[60:61] op_sel_hi:[0,1]
	v_pk_mul_f32 v[62:63], v[70:71], v[62:63] op_sel_hi:[0,1]
	v_pk_mul_f32 v[60:61], v[8:9], v[60:61]
	v_pk_mul_f32 v[62:63], v[10:11], v[62:63]
	global_store_dwordx4 v[68:69], v[60:63], off offset:1024
	v_pk_mul_f32 v[64:65], v[70:71], v[64:65] op_sel_hi:[0,1]
	v_pk_mul_f32 v[64:65], v[12:13], v[64:65]
	v_lshlrev_b32_e32 v60, 16, v56
	v_and_b32_e32 v61, 0xffff0000, v56
	v_lshlrev_b32_e32 v56, 16, v57
	v_and_b32_e32 v57, 0xffff0000, v57
	v_pk_mul_f32 v[56:57], v[70:71], v[56:57] op_sel_hi:[0,1]
	v_pk_mul_f32 v[62:63], v[6:7], v[56:57]
	v_lshlrev_b32_e32 v56, 16, v58
	v_and_b32_e32 v57, 0xffff0000, v58
	v_lshlrev_b32_e32 v58, 16, v59
	v_and_b32_e32 v59, 0xffff0000, v59
	v_pk_mul_f32 v[60:61], v[70:71], v[60:61] op_sel_hi:[0,1]
	v_pk_mul_f32 v[56:57], v[70:71], v[56:57] op_sel_hi:[0,1]
	v_pk_mul_f32 v[58:59], v[70:71], v[58:59] op_sel_hi:[0,1]
	v_pk_mul_f32 v[60:61], v[4:5], v[60:61]
	v_pk_mul_f32 v[56:57], v[0:1], v[56:57]
	v_pk_mul_f32 v[58:59], v[2:3], v[58:59]
	v_cmp_lt_i32_e32 vcc, s14, v114
	global_store_dwordx4 v[68:69], v[64:67], off
	global_store_dwordx4 v[68:69], v[60:63], off offset:2048
	global_store_dwordx4 v[68:69], v[56:59], off offset:3072
	s_and_saveexec_b64 s[0:1], vcc
	s_xor_b64 s[0:1], exec, s[0:1]
	v_add_u32_e32 v56, 4, v88
	v_mov_b32_e32 v57, v89
	v_lshlrev_b64 v[56:57], 10, v[56:57]
	v_lshl_add_u64 v[56:57], v[56:57], 0, s[6:7]
	s_andn2_saveexec_b64 s[0:1], s[0:1]
	v_lshlrev_b64 v[56:57], 10, v[102:103]
	s_or_b64 exec, exec, s[0:1]
	v_fmamk_f32 v58, v117, 0x3a800000, v115
	v_mul_f32_e32 v59, 0x4b800000, v58
	v_cmp_gt_f32_e64 s[0:1], s13, v58
	v_lshl_add_u64 v[60:61], v[56:57], 2, v[92:93]
	v_lshlrev_b32_e32 v56, 16, v52
	v_cndmask_b32_e64 v58, v58, v59, s[0:1]
	v_rsq_f32_e32 v58, v58
	s_nop 0
	v_mul_f32_e32 v57, 0x45800000, v58
	v_cndmask_b32_e64 v62, v58, v57, s[0:1]
	v_and_b32_e32 v57, 0xffff0000, v52
	v_lshlrev_b32_e32 v52, 16, v53
	v_and_b32_e32 v53, 0xffff0000, v53
	v_pk_mul_f32 v[52:53], v[62:63], v[52:53] op_sel_hi:[0,1]
	v_pk_mul_f32 v[58:59], v[14:15], v[52:53]
	v_lshlrev_b32_e32 v52, 16, v54
	v_and_b32_e32 v53, 0xffff0000, v54
	v_lshlrev_b32_e32 v54, 16, v55
	v_and_b32_e32 v55, 0xffff0000, v55
	v_pk_mul_f32 v[52:53], v[62:63], v[52:53] op_sel_hi:[0,1]
	v_pk_mul_f32 v[54:55], v[62:63], v[54:55] op_sel_hi:[0,1]
	v_pk_mul_f32 v[52:53], v[8:9], v[52:53]
	v_pk_mul_f32 v[54:55], v[10:11], v[54:55]
	global_store_dwordx4 v[60:61], v[52:55], off offset:1024
	v_pk_mul_f32 v[56:57], v[62:63], v[56:57] op_sel_hi:[0,1]
	v_pk_mul_f32 v[56:57], v[12:13], v[56:57]
	v_lshlrev_b32_e32 v52, 16, v48
	v_and_b32_e32 v53, 0xffff0000, v48
	v_lshlrev_b32_e32 v48, 16, v49
	v_and_b32_e32 v49, 0xffff0000, v49
	v_pk_mul_f32 v[48:49], v[62:63], v[48:49] op_sel_hi:[0,1]
	v_pk_mul_f32 v[54:55], v[6:7], v[48:49]
	v_lshlrev_b32_e32 v48, 16, v50
	v_and_b32_e32 v49, 0xffff0000, v50
	v_lshlrev_b32_e32 v50, 16, v51
	v_and_b32_e32 v51, 0xffff0000, v51
	v_pk_mul_f32 v[52:53], v[62:63], v[52:53] op_sel_hi:[0,1]
	v_pk_mul_f32 v[48:49], v[62:63], v[48:49] op_sel_hi:[0,1]
	v_pk_mul_f32 v[50:51], v[62:63], v[50:51] op_sel_hi:[0,1]
	v_pk_mul_f32 v[52:53], v[4:5], v[52:53]
	v_pk_mul_f32 v[48:49], v[0:1], v[48:49]
	v_pk_mul_f32 v[50:51], v[2:3], v[50:51]
	global_store_dwordx4 v[60:61], v[56:59], off
	global_store_dwordx4 v[60:61], v[52:55], off offset:2048
	global_store_dwordx4 v[60:61], v[48:51], off offset:3072
	s_and_saveexec_b64 s[0:1], vcc
	s_xor_b64 s[0:1], exec, s[0:1]
	v_add_u32_e32 v48, 5, v88
	v_mov_b32_e32 v49, v89
	v_lshlrev_b64 v[48:49], 10, v[48:49]
	v_lshl_add_u64 v[48:49], v[48:49], 0, s[6:7]
	s_andn2_saveexec_b64 s[0:1], s[0:1]
	v_lshlrev_b64 v[48:49], 10, v[100:101]
	s_or_b64 exec, exec, s[0:1]
	v_fmamk_f32 v50, v99, 0x3a800000, v115
	v_mul_f32_e32 v51, 0x4b800000, v50
	v_cmp_gt_f32_e64 s[0:1], s13, v50
	v_lshl_add_u64 v[52:53], v[48:49], 2, v[92:93]
	v_lshlrev_b32_e32 v48, 16, v44
	v_cndmask_b32_e64 v50, v50, v51, s[0:1]
	v_rsq_f32_e32 v50, v50
	s_nop 0
	v_mul_f32_e32 v49, 0x45800000, v50
	v_cndmask_b32_e64 v54, v50, v49, s[0:1]
	v_and_b32_e32 v49, 0xffff0000, v44
	v_lshlrev_b32_e32 v44, 16, v45
	v_and_b32_e32 v45, 0xffff0000, v45
	v_pk_mul_f32 v[44:45], v[54:55], v[44:45] op_sel_hi:[0,1]
	v_pk_mul_f32 v[50:51], v[14:15], v[44:45]
	v_lshlrev_b32_e32 v44, 16, v46
	v_and_b32_e32 v45, 0xffff0000, v46
	v_lshlrev_b32_e32 v46, 16, v47
	v_and_b32_e32 v47, 0xffff0000, v47
	v_pk_mul_f32 v[44:45], v[54:55], v[44:45] op_sel_hi:[0,1]
	v_pk_mul_f32 v[46:47], v[54:55], v[46:47] op_sel_hi:[0,1]
	v_pk_mul_f32 v[44:45], v[8:9], v[44:45]
	v_pk_mul_f32 v[46:47], v[10:11], v[46:47]
	global_store_dwordx4 v[52:53], v[44:47], off offset:1024
	v_pk_mul_f32 v[48:49], v[54:55], v[48:49] op_sel_hi:[0,1]
	v_pk_mul_f32 v[48:49], v[12:13], v[48:49]
	v_lshlrev_b32_e32 v44, 16, v40
	v_and_b32_e32 v45, 0xffff0000, v40
	v_lshlrev_b32_e32 v40, 16, v41
	v_and_b32_e32 v41, 0xffff0000, v41
	v_pk_mul_f32 v[40:41], v[54:55], v[40:41] op_sel_hi:[0,1]
	v_pk_mul_f32 v[46:47], v[6:7], v[40:41]
	v_lshlrev_b32_e32 v40, 16, v42
	v_and_b32_e32 v41, 0xffff0000, v42
	v_lshlrev_b32_e32 v42, 16, v43
	v_and_b32_e32 v43, 0xffff0000, v43
	v_pk_mul_f32 v[44:45], v[54:55], v[44:45] op_sel_hi:[0,1]
	v_pk_mul_f32 v[40:41], v[54:55], v[40:41] op_sel_hi:[0,1]
	v_pk_mul_f32 v[42:43], v[54:55], v[42:43] op_sel_hi:[0,1]
	v_pk_mul_f32 v[44:45], v[4:5], v[44:45]
	v_pk_mul_f32 v[40:41], v[0:1], v[40:41]
	v_pk_mul_f32 v[42:43], v[2:3], v[42:43]
	v_cmp_gt_i32_e64 s[0:1], s15, v114
	global_store_dwordx4 v[52:53], v[48:51], off
	global_store_dwordx4 v[52:53], v[44:47], off offset:2048
	global_store_dwordx4 v[52:53], v[40:43], off offset:3072
	s_and_saveexec_b64 s[8:9], s[0:1]
	s_cbranch_execz .LBB0_1513
	s_and_saveexec_b64 s[0:1], vcc
	s_xor_b64 s[0:1], exec, s[0:1]
	v_add_u32_e32 v40, 6, v88
	v_mov_b32_e32 v41, v89
	v_lshlrev_b64 v[40:41], 10, v[40:41]
	v_lshl_add_u64 v[40:41], v[40:41], 0, s[6:7]
	s_andn2_saveexec_b64 s[0:1], s[0:1]
	v_ashrrev_i32_e32 v99, 31, v98
	v_lshlrev_b64 v[40:41], 10, v[98:99]
	s_or_b64 exec, exec, s[0:1]
	v_fmamk_f32 v42, v97, 0x3a800000, v115
	v_mul_f32_e32 v43, 0x4b800000, v42
	v_cmp_gt_f32_e64 s[0:1], s13, v42
	v_lshl_add_u64 v[44:45], v[40:41], 2, v[92:93]
	v_lshlrev_b32_e32 v40, 16, v36
	v_cndmask_b32_e64 v42, v42, v43, s[0:1]
	v_rsq_f32_e32 v42, v42
	s_nop 0
	v_mul_f32_e32 v41, 0x45800000, v42
	v_cndmask_b32_e64 v46, v42, v41, s[0:1]
	v_and_b32_e32 v41, 0xffff0000, v36
	v_lshlrev_b32_e32 v36, 16, v37
	v_and_b32_e32 v37, 0xffff0000, v37
	v_pk_mul_f32 v[36:37], v[46:47], v[36:37] op_sel_hi:[0,1]
	v_pk_mul_f32 v[42:43], v[14:15], v[36:37]
	v_lshlrev_b32_e32 v36, 16, v38
	v_and_b32_e32 v37, 0xffff0000, v38
	v_lshlrev_b32_e32 v38, 16, v39
	v_and_b32_e32 v39, 0xffff0000, v39
	v_pk_mul_f32 v[36:37], v[46:47], v[36:37] op_sel_hi:[0,1]
	v_pk_mul_f32 v[38:39], v[46:47], v[38:39] op_sel_hi:[0,1]
	v_pk_mul_f32 v[36:37], v[8:9], v[36:37]
	v_pk_mul_f32 v[38:39], v[10:11], v[38:39]
	global_store_dwordx4 v[44:45], v[36:39], off offset:1024
	v_pk_mul_f32 v[40:41], v[46:47], v[40:41] op_sel_hi:[0,1]
	v_pk_mul_f32 v[40:41], v[12:13], v[40:41]
	v_lshlrev_b32_e32 v36, 16, v32
	v_and_b32_e32 v37, 0xffff0000, v32
	v_lshlrev_b32_e32 v32, 16, v33
	v_and_b32_e32 v33, 0xffff0000, v33
	v_pk_mul_f32 v[32:33], v[46:47], v[32:33] op_sel_hi:[0,1]
	v_pk_mul_f32 v[38:39], v[6:7], v[32:33]
	v_lshlrev_b32_e32 v32, 16, v34
	v_and_b32_e32 v33, 0xffff0000, v34
	v_lshlrev_b32_e32 v34, 16, v35
	v_and_b32_e32 v35, 0xffff0000, v35
	v_pk_mul_f32 v[36:37], v[46:47], v[36:37] op_sel_hi:[0,1]
	v_pk_mul_f32 v[32:33], v[46:47], v[32:33] op_sel_hi:[0,1]
	v_pk_mul_f32 v[34:35], v[46:47], v[34:35] op_sel_hi:[0,1]
	v_pk_mul_f32 v[36:37], v[4:5], v[36:37]
	v_pk_mul_f32 v[32:33], v[0:1], v[32:33]
	v_pk_mul_f32 v[34:35], v[2:3], v[34:35]
	global_store_dwordx4 v[44:45], v[40:43], off
	global_store_dwordx4 v[44:45], v[36:39], off offset:2048
	global_store_dwordx4 v[44:45], v[32:35], off offset:3072
	s_and_saveexec_b64 s[0:1], vcc
	s_xor_b64 s[0:1], exec, s[0:1]
	v_add_u32_e32 v32, 7, v88
	v_mov_b32_e32 v33, v89
	v_lshlrev_b64 v[32:33], 10, v[32:33]
	v_lshl_add_u64 v[32:33], v[32:33], 0, s[6:7]
	s_andn2_saveexec_b64 s[0:1], s[0:1]
	v_ashrrev_i32_e32 v97, 31, v96
	v_lshlrev_b64 v[32:33], 10, v[96:97]
	s_or_b64 exec, exec, s[0:1]
	v_fmamk_f32 v34, v95, 0x3a800000, v115
	v_mul_f32_e32 v35, 0x4b800000, v34
	v_cmp_gt_f32_e64 s[0:1], s13, v34
	v_lshl_add_u64 v[36:37], v[32:33], 2, v[92:93]
	v_lshlrev_b32_e32 v32, 16, v28
	v_cndmask_b32_e64 v34, v34, v35, s[0:1]
	v_rsq_f32_e32 v34, v34
	s_nop 0
	v_mul_f32_e32 v33, 0x45800000, v34
	v_cndmask_b32_e64 v38, v34, v33, s[0:1]
	v_and_b32_e32 v33, 0xffff0000, v28
	v_lshlrev_b32_e32 v28, 16, v29
	v_and_b32_e32 v29, 0xffff0000, v29
	v_pk_mul_f32 v[28:29], v[38:39], v[28:29] op_sel_hi:[0,1]
	v_pk_mul_f32 v[34:35], v[14:15], v[28:29]
	v_lshlrev_b32_e32 v28, 16, v30
	v_and_b32_e32 v29, 0xffff0000, v30
	v_lshlrev_b32_e32 v30, 16, v31
	v_and_b32_e32 v31, 0xffff0000, v31
	v_pk_mul_f32 v[28:29], v[38:39], v[28:29] op_sel_hi:[0,1]
	v_pk_mul_f32 v[30:31], v[38:39], v[30:31] op_sel_hi:[0,1]
	v_pk_mul_f32 v[28:29], v[8:9], v[28:29]
	v_pk_mul_f32 v[30:31], v[10:11], v[30:31]
	global_store_dwordx4 v[36:37], v[28:31], off offset:1024
	v_pk_mul_f32 v[32:33], v[38:39], v[32:33] op_sel_hi:[0,1]
	v_pk_mul_f32 v[32:33], v[12:13], v[32:33]
	v_lshlrev_b32_e32 v28, 16, v24
	v_and_b32_e32 v29, 0xffff0000, v24
	v_lshlrev_b32_e32 v24, 16, v25
	v_and_b32_e32 v25, 0xffff0000, v25
	v_pk_mul_f32 v[24:25], v[38:39], v[24:25] op_sel_hi:[0,1]
	v_pk_mul_f32 v[30:31], v[6:7], v[24:25]
	v_lshlrev_b32_e32 v24, 16, v26
	v_and_b32_e32 v25, 0xffff0000, v26
	v_lshlrev_b32_e32 v26, 16, v27
	v_and_b32_e32 v27, 0xffff0000, v27
	v_pk_mul_f32 v[28:29], v[38:39], v[28:29] op_sel_hi:[0,1]
	v_pk_mul_f32 v[24:25], v[38:39], v[24:25] op_sel_hi:[0,1]
	v_pk_mul_f32 v[26:27], v[38:39], v[26:27] op_sel_hi:[0,1]
	v_pk_mul_f32 v[28:29], v[4:5], v[28:29]
	v_pk_mul_f32 v[24:25], v[0:1], v[24:25]
	v_pk_mul_f32 v[26:27], v[2:3], v[26:27]
	global_store_dwordx4 v[36:37], v[32:35], off
	global_store_dwordx4 v[36:37], v[28:31], off offset:2048
	global_store_dwordx4 v[36:37], v[24:27], off offset:3072
	s_and_saveexec_b64 s[0:1], vcc
	s_xor_b64 s[0:1], exec, s[0:1]
	v_add_u32_e32 v24, 8, v88
	v_mov_b32_e32 v25, v89
	v_lshlrev_b64 v[24:25], 10, v[24:25]
	v_lshl_add_u64 v[24:25], v[24:25], 0, s[6:7]
	s_andn2_saveexec_b64 s[0:1], s[0:1]
	s_cbranch_execz .LBB0_1512
	v_ashrrev_i32_e32 v95, 31, v94
	v_lshlrev_b64 v[24:25], 10, v[94:95]
	s_branch .LBB0_1512
